# gate phase g_low: hoist 32 x loads per token pair, counted vmcnt waits (stacked on v1)
# speedup vs baseline: 1.0054x; 1.0054x over previous
; #define LAS __attribute__((address_space(3)))
; DI void gla_gate_phase(int wv, LAS unsigned char* lds, const float* x, const float* w_in, const float* w2, const float* bg, const bf16_t* qk1,
;                        bf16_t* qd, bf16_t* ki, bf16_t* kst, float* decay, bf16_t* sbuf) {
;     ...
;             for (int i = 0; i < 16; ++i) { const int k = lane + 64 * i; const float x0 = x[t0 * DM + k], x1 = x[(t0 + 1) * DM + k];
; #pragma unroll
;                 for (int q = 0; q < 4; ++q) { const f32x4 w = *(const LAS f32x4*)(wg + k * 16 + 4 * q);
;                     a0[4 * q] += x0 * w.x; a0[4 * q + 1] += x0 * w.y; a0[4 * q + 2] += x0 * w.z; a0[4 * q + 3] += x0 * w.w;
;                     a1[4 * q] += x1 * w.x; a1[4 * q + 1] += x1 * w.y; a1[4 * q + 2] += x1 * w.z; a1[4 * q + 3] += x1 * w.w; } }
.LBB0_143:
	v_or_b32_e32 v8, v2, v50
	v_mov_b32_e32 v9, v3
	v_lshl_add_u64 v[8:9], v[8:9], 2, s[52:53]
	v_mov_b32_e32 v168, v8
	v_mov_b32_e32 v169, v9
	global_load_dword v176, v[4:5], off
	global_load_dword v200, v[168:169], off
	global_load_dword v177, v[4:5], off offset:256
	global_load_dword v201, v[168:169], off offset:256
	global_load_dword v178, v[4:5], off offset:512
	global_load_dword v202, v[168:169], off offset:512
	global_load_dword v179, v[4:5], off offset:768
	global_load_dword v203, v[168:169], off offset:768
	global_load_dword v180, v[4:5], off offset:1024
	global_load_dword v204, v[168:169], off offset:1024
	global_load_dword v181, v[4:5], off offset:1280
	global_load_dword v205, v[168:169], off offset:1280
	global_load_dword v182, v[4:5], off offset:1536
	global_load_dword v206, v[168:169], off offset:1536
	global_load_dword v183, v[4:5], off offset:1792
	global_load_dword v207, v[168:169], off offset:1792
	global_load_dword v184, v[4:5], off offset:2048
	global_load_dword v208, v[168:169], off offset:2048
	global_load_dword v185, v[4:5], off offset:2304
	global_load_dword v209, v[168:169], off offset:2304
	global_load_dword v186, v[4:5], off offset:2560
	global_load_dword v210, v[168:169], off offset:2560
	global_load_dword v187, v[4:5], off offset:2816
	global_load_dword v211, v[168:169], off offset:2816
	global_load_dword v188, v[4:5], off offset:3072
	global_load_dword v212, v[168:169], off offset:3072
	global_load_dword v189, v[4:5], off offset:3328
	global_load_dword v213, v[168:169], off offset:3328
	global_load_dword v190, v[4:5], off offset:3584
	global_load_dword v214, v[168:169], off offset:3584
	global_load_dword v191, v[4:5], off offset:3840
	global_load_dword v215, v[168:169], off offset:3840
	s_nop 0
	s_waitcnt lgkmcnt(14)
	s_nop 0
	v_add_u32_e32 v16, 0, v49
	ds_read_b128 v[8:11], v16
	ds_read_b128 v[12:15], v16 offset:16
	ds_read_b128 v[116:119], v16 offset:32
	ds_read_b128 v[120:123], v16 offset:48
	s_waitcnt vmcnt(31) lgkmcnt(1)
	v_fma_f32 v98, v176, v116, 0
	v_fma_f32 v96, v176, v117, 0
	s_waitcnt vmcnt(30)
	v_fma_f32 v97, v200, v116, 0
	v_fma_f32 v95, v200, v117, 0
	v_or_b32_e32 v116, v2, v52
	v_mov_b32_e32 v117, v3
	v_lshl_add_u64 v[116:117], v[116:117], 2, s[52:53]
	v_fma_f32 v114, v176, v8, 0
	v_fma_f32 v112, v176, v9, 0
	v_fma_f32 v110, v176, v10, 0
	v_fma_f32 v108, v176, v11, 0
	v_fma_f32 v113, v200, v8, 0
	v_fma_f32 v111, v200, v9, 0
	v_fma_f32 v109, v200, v10, 0
	v_fma_f32 v107, v200, v11, 0
	v_fma_f32 v106, v176, v12, 0
	v_fma_f32 v104, v176, v13, 0
	v_fma_f32 v102, v176, v14, 0
	v_fma_f32 v100, v176, v15, 0
	v_fma_f32 v105, v200, v12, 0
	v_fma_f32 v103, v200, v13, 0
	v_fma_f32 v101, v200, v14, 0
	v_fma_f32 v99, v200, v15, 0
	v_fma_f32 v93, v176, v118, 0
	v_fma_f32 v16, v176, v119, 0
	v_fma_f32 v17, v200, v118, 0
	v_fma_f32 v15, v200, v119, 0
	s_waitcnt lgkmcnt(0)
	v_fma_f32 v14, v176, v120, 0
	v_fma_f32 v12, v176, v121, 0
	v_fma_f32 v10, v176, v122, 0
	v_fma_f32 v8, v176, v123, 0
	v_fma_f32 v13, v200, v120, 0
	v_fma_f32 v11, v200, v121, 0
	v_fma_f32 v9, v200, v122, 0
	v_fma_f32 v7, v200, v123, 0
	s_nop 0
	s_nop 0
	ds_read_b128 v[116:119], v53
	ds_read_b128 v[120:123], v53 offset:16
	ds_read_b128 v[124:127], v53 offset:32
	ds_read_b128 v[128:131], v53 offset:48
	s_waitcnt vmcnt(29) lgkmcnt(3)
	v_fmac_f32_e32 v114, v177, v116
	v_fmac_f32_e32 v112, v177, v117
	s_waitcnt vmcnt(28)
	v_fmac_f32_e32 v113, v201, v116
	v_fmac_f32_e32 v111, v201, v117
	v_or_b32_e32 v116, v2, v54
	v_mov_b32_e32 v117, v3
	v_lshl_add_u64 v[116:117], v[116:117], 2, s[52:53]
	v_fmac_f32_e32 v110, v177, v118
	v_fmac_f32_e32 v108, v177, v119
	v_fmac_f32_e32 v109, v201, v118
	v_fmac_f32_e32 v107, v201, v119
	s_waitcnt lgkmcnt(2)
	v_fmac_f32_e32 v106, v177, v120
	v_fmac_f32_e32 v104, v177, v121
	v_fmac_f32_e32 v102, v177, v122
	v_fmac_f32_e32 v100, v177, v123
	v_fmac_f32_e32 v105, v201, v120
	v_fmac_f32_e32 v103, v201, v121
	v_fmac_f32_e32 v101, v201, v122
	v_fmac_f32_e32 v99, v201, v123
	s_waitcnt lgkmcnt(1)
	v_fmac_f32_e32 v98, v177, v124
	v_fmac_f32_e32 v96, v177, v125
	v_fmac_f32_e32 v93, v177, v126
	v_fmac_f32_e32 v16, v177, v127
	v_fmac_f32_e32 v97, v201, v124
	v_fmac_f32_e32 v95, v201, v125
	v_fmac_f32_e32 v17, v201, v126
	v_fmac_f32_e32 v15, v201, v127
	s_waitcnt lgkmcnt(0)
	v_fmac_f32_e32 v14, v177, v128
	v_fmac_f32_e32 v12, v177, v129
	v_fmac_f32_e32 v10, v177, v130
	v_fmac_f32_e32 v8, v177, v131
	v_fmac_f32_e32 v13, v201, v128
	v_fmac_f32_e32 v11, v201, v129
	v_fmac_f32_e32 v9, v201, v130
	v_fmac_f32_e32 v7, v201, v131
	s_nop 0
	s_nop 0
	ds_read_b128 v[116:119], v55
	ds_read_b128 v[120:123], v55 offset:16
	ds_read_b128 v[124:127], v55 offset:32
	ds_read_b128 v[128:131], v55 offset:48
	s_waitcnt vmcnt(27) lgkmcnt(3)
	v_fmac_f32_e32 v114, v178, v116
	v_fmac_f32_e32 v112, v178, v117
	s_waitcnt vmcnt(26)
	v_fmac_f32_e32 v113, v202, v116
	v_fmac_f32_e32 v111, v202, v117
	v_or_b32_e32 v116, v2, v56
	v_mov_b32_e32 v117, v3
	v_lshl_add_u64 v[116:117], v[116:117], 2, s[52:53]
	v_fmac_f32_e32 v110, v178, v118
	v_fmac_f32_e32 v108, v178, v119
	v_fmac_f32_e32 v109, v202, v118
	v_fmac_f32_e32 v107, v202, v119
	s_waitcnt lgkmcnt(2)
	v_fmac_f32_e32 v106, v178, v120
	v_fmac_f32_e32 v104, v178, v121
	v_fmac_f32_e32 v102, v178, v122
	v_fmac_f32_e32 v100, v178, v123
	v_fmac_f32_e32 v105, v202, v120
	v_fmac_f32_e32 v103, v202, v121
	v_fmac_f32_e32 v101, v202, v122
	v_fmac_f32_e32 v99, v202, v123
	s_waitcnt lgkmcnt(1)
	v_fmac_f32_e32 v98, v178, v124
	v_fmac_f32_e32 v96, v178, v125
	v_fmac_f32_e32 v93, v178, v126
	v_fmac_f32_e32 v16, v178, v127
	v_fmac_f32_e32 v97, v202, v124
	v_fmac_f32_e32 v95, v202, v125
	v_fmac_f32_e32 v17, v202, v126
	v_fmac_f32_e32 v15, v202, v127
	s_waitcnt lgkmcnt(0)
; #define LAS __attribute__((address_space(3)))
; DI void gla_gate_phase(int wv, LAS unsigned char* lds, const float* x, const float* w_in, const float* w2, const float* bg, const bf16_t* qk1,
;                        bf16_t* qd, bf16_t* ki, bf16_t* kst, float* decay, bf16_t* sbuf) {
;     ...
;             for (int i = 0; i < 16; ++i) { const int k = lane + 64 * i; const float x0 = x[t0 * DM + k], x1 = x[(t0 + 1) * DM + k];
; #pragma unroll
;                 for (int q = 0; q < 4; ++q) { const f32x4 w = *(const LAS f32x4*)(wg + k * 16 + 4 * q);
;                     a0[4 * q] += x0 * w.x; a0[4 * q + 1] += x0 * w.y; a0[4 * q + 2] += x0 * w.z; a0[4 * q + 3] += x0 * w.w;
;                     a1[4 * q] += x1 * w.x; a1[4 * q + 1] += x1 * w.y; a1[4 * q + 2] += x1 * w.z; a1[4 * q + 3] += x1 * w.w; } }
	v_fmac_f32_e32 v14, v178, v128
	v_fmac_f32_e32 v12, v178, v129
	v_fmac_f32_e32 v10, v178, v130
	v_fmac_f32_e32 v8, v178, v131
	v_fmac_f32_e32 v13, v202, v128
	v_fmac_f32_e32 v11, v202, v129
	v_fmac_f32_e32 v9, v202, v130
	v_fmac_f32_e32 v7, v202, v131
	s_nop 0
	s_nop 0
	ds_read_b128 v[116:119], v57
	ds_read_b128 v[120:123], v57 offset:16
	ds_read_b128 v[124:127], v57 offset:32
	ds_read_b128 v[128:131], v57 offset:48
	s_waitcnt vmcnt(25) lgkmcnt(3)
	v_fmac_f32_e32 v114, v179, v116
	v_fmac_f32_e32 v112, v179, v117
	s_waitcnt vmcnt(24)
	v_fmac_f32_e32 v113, v203, v116
	v_fmac_f32_e32 v111, v203, v117
	v_or_b32_e32 v116, v2, v58
	v_mov_b32_e32 v117, v3
	v_lshl_add_u64 v[116:117], v[116:117], 2, s[52:53]
	v_fmac_f32_e32 v110, v179, v118
	v_fmac_f32_e32 v108, v179, v119
	v_fmac_f32_e32 v109, v203, v118
	v_fmac_f32_e32 v107, v203, v119
	s_waitcnt lgkmcnt(2)
	v_fmac_f32_e32 v106, v179, v120
	v_fmac_f32_e32 v104, v179, v121
	v_fmac_f32_e32 v102, v179, v122
	v_fmac_f32_e32 v100, v179, v123
	v_fmac_f32_e32 v105, v203, v120
	v_fmac_f32_e32 v103, v203, v121
	v_fmac_f32_e32 v101, v203, v122
	v_fmac_f32_e32 v99, v203, v123
	s_waitcnt lgkmcnt(1)
	v_fmac_f32_e32 v98, v179, v124
	v_fmac_f32_e32 v96, v179, v125
	v_fmac_f32_e32 v93, v179, v126
	v_fmac_f32_e32 v16, v179, v127
	v_fmac_f32_e32 v97, v203, v124
	v_fmac_f32_e32 v95, v203, v125
	v_fmac_f32_e32 v17, v203, v126
	v_fmac_f32_e32 v15, v203, v127
	s_waitcnt lgkmcnt(0)
	v_fmac_f32_e32 v14, v179, v128
	v_fmac_f32_e32 v12, v179, v129
	v_fmac_f32_e32 v10, v179, v130
	v_fmac_f32_e32 v8, v179, v131
	v_fmac_f32_e32 v13, v203, v128
	v_fmac_f32_e32 v11, v203, v129
	v_fmac_f32_e32 v9, v203, v130
	v_fmac_f32_e32 v7, v203, v131
	s_nop 0
	s_nop 0
	ds_read_b128 v[116:119], v59
	ds_read_b128 v[120:123], v59 offset:16
	ds_read_b128 v[124:127], v59 offset:32
	ds_read_b128 v[128:131], v59 offset:48
	s_waitcnt vmcnt(23) lgkmcnt(3)
	v_fmac_f32_e32 v114, v180, v116
	v_fmac_f32_e32 v112, v180, v117
	s_waitcnt vmcnt(22)
	v_fmac_f32_e32 v113, v204, v116
	v_fmac_f32_e32 v111, v204, v117
	v_or_b32_e32 v116, v2, v60
	v_mov_b32_e32 v117, v3
	v_lshl_add_u64 v[116:117], v[116:117], 2, s[52:53]
	v_fmac_f32_e32 v110, v180, v118
	v_fmac_f32_e32 v108, v180, v119
	v_fmac_f32_e32 v109, v204, v118
	v_fmac_f32_e32 v107, v204, v119
	s_waitcnt lgkmcnt(2)
	v_fmac_f32_e32 v106, v180, v120
	v_fmac_f32_e32 v104, v180, v121
	v_fmac_f32_e32 v102, v180, v122
	v_fmac_f32_e32 v100, v180, v123
	v_fmac_f32_e32 v105, v204, v120
	v_fmac_f32_e32 v103, v204, v121
	v_fmac_f32_e32 v101, v204, v122
	v_fmac_f32_e32 v99, v204, v123
	s_waitcnt lgkmcnt(1)
	v_fmac_f32_e32 v98, v180, v124
	v_fmac_f32_e32 v96, v180, v125
	v_fmac_f32_e32 v93, v180, v126
	v_fmac_f32_e32 v16, v180, v127
	v_fmac_f32_e32 v97, v204, v124
	v_fmac_f32_e32 v95, v204, v125
	v_fmac_f32_e32 v17, v204, v126
	v_fmac_f32_e32 v15, v204, v127
	s_waitcnt lgkmcnt(0)
	v_fmac_f32_e32 v14, v180, v128
	v_fmac_f32_e32 v12, v180, v129
	v_fmac_f32_e32 v10, v180, v130
	v_fmac_f32_e32 v8, v180, v131
	v_fmac_f32_e32 v13, v204, v128
	v_fmac_f32_e32 v11, v204, v129
	v_fmac_f32_e32 v9, v204, v130
	v_fmac_f32_e32 v7, v204, v131
	s_nop 0
	s_nop 0
	ds_read_b128 v[116:119], v61
	ds_read_b128 v[120:123], v61 offset:16
	ds_read_b128 v[124:127], v61 offset:32
	ds_read_b128 v[128:131], v61 offset:48
	s_waitcnt vmcnt(21) lgkmcnt(3)
	v_fmac_f32_e32 v114, v181, v116
	v_fmac_f32_e32 v112, v181, v117
	s_waitcnt vmcnt(20)
	v_fmac_f32_e32 v113, v205, v116
	v_fmac_f32_e32 v111, v205, v117
	v_or_b32_e32 v116, v2, v62
	v_mov_b32_e32 v117, v3
	v_lshl_add_u64 v[116:117], v[116:117], 2, s[52:53]
	v_fmac_f32_e32 v110, v181, v118
	v_fmac_f32_e32 v108, v181, v119
	v_fmac_f32_e32 v109, v205, v118
	v_fmac_f32_e32 v107, v205, v119
	s_waitcnt lgkmcnt(2)
	v_fmac_f32_e32 v106, v181, v120
	v_fmac_f32_e32 v104, v181, v121
	v_fmac_f32_e32 v102, v181, v122
	v_fmac_f32_e32 v100, v181, v123
	v_fmac_f32_e32 v105, v205, v120
	v_fmac_f32_e32 v103, v205, v121
	v_fmac_f32_e32 v101, v205, v122
	v_fmac_f32_e32 v99, v205, v123
	s_waitcnt lgkmcnt(1)
	v_fmac_f32_e32 v98, v181, v124
	v_fmac_f32_e32 v96, v181, v125
	v_fmac_f32_e32 v93, v181, v126
	v_fmac_f32_e32 v16, v181, v127
	v_fmac_f32_e32 v97, v205, v124
	v_fmac_f32_e32 v95, v205, v125
	v_fmac_f32_e32 v17, v205, v126
	v_fmac_f32_e32 v15, v205, v127
	s_waitcnt lgkmcnt(0)
	v_fmac_f32_e32 v14, v181, v128
	v_fmac_f32_e32 v12, v181, v129
	v_fmac_f32_e32 v10, v181, v130
	v_fmac_f32_e32 v8, v181, v131
	v_fmac_f32_e32 v13, v205, v128
	v_fmac_f32_e32 v11, v205, v129
	v_fmac_f32_e32 v9, v205, v130
	v_fmac_f32_e32 v7, v205, v131
	s_nop 0
	s_nop 0
	ds_read_b128 v[116:119], v63
	ds_read_b128 v[120:123], v63 offset:16
	ds_read_b128 v[124:127], v63 offset:32
	ds_read_b128 v[128:131], v63 offset:48
	s_waitcnt vmcnt(19) lgkmcnt(3)
	v_fmac_f32_e32 v114, v182, v116
	v_fmac_f32_e32 v112, v182, v117
	s_waitcnt vmcnt(18)
	v_fmac_f32_e32 v113, v206, v116
	v_fmac_f32_e32 v111, v206, v117
	v_or_b32_e32 v116, v2, v64
	v_mov_b32_e32 v117, v3
	v_lshl_add_u64 v[116:117], v[116:117], 2, s[52:53]
	v_fmac_f32_e32 v110, v182, v118
	v_fmac_f32_e32 v108, v182, v119
	v_fmac_f32_e32 v109, v206, v118
	v_fmac_f32_e32 v107, v206, v119
	s_waitcnt lgkmcnt(2)
	v_fmac_f32_e32 v106, v182, v120
	v_fmac_f32_e32 v104, v182, v121
	v_fmac_f32_e32 v102, v182, v122
	v_fmac_f32_e32 v100, v182, v123
	v_fmac_f32_e32 v105, v206, v120
	v_fmac_f32_e32 v103, v206, v121
	v_fmac_f32_e32 v101, v206, v122
	v_fmac_f32_e32 v99, v206, v123
	s_waitcnt lgkmcnt(1)
	v_fmac_f32_e32 v98, v182, v124
	v_fmac_f32_e32 v96, v182, v125
	v_fmac_f32_e32 v93, v182, v126
	v_fmac_f32_e32 v16, v182, v127
	v_fmac_f32_e32 v97, v206, v124
	v_fmac_f32_e32 v95, v206, v125
	v_fmac_f32_e32 v17, v206, v126
	v_fmac_f32_e32 v15, v206, v127
	s_waitcnt lgkmcnt(0)
; #define LAS __attribute__((address_space(3)))
; DI void gla_gate_phase(int wv, LAS unsigned char* lds, const float* x, const float* w_in, const float* w2, const float* bg, const bf16_t* qk1,
;                        bf16_t* qd, bf16_t* ki, bf16_t* kst, float* decay, bf16_t* sbuf) {
;     ...
;             for (int i = 0; i < 16; ++i) { const int k = lane + 64 * i; const float x0 = x[t0 * DM + k], x1 = x[(t0 + 1) * DM + k];
; #pragma unroll
;                 for (int q = 0; q < 4; ++q) { const f32x4 w = *(const LAS f32x4*)(wg + k * 16 + 4 * q);
;                     a0[4 * q] += x0 * w.x; a0[4 * q + 1] += x0 * w.y; a0[4 * q + 2] += x0 * w.z; a0[4 * q + 3] += x0 * w.w;
;                     a1[4 * q] += x1 * w.x; a1[4 * q + 1] += x1 * w.y; a1[4 * q + 2] += x1 * w.z; a1[4 * q + 3] += x1 * w.w; } }
	v_fmac_f32_e32 v14, v182, v128
	v_fmac_f32_e32 v12, v182, v129
	v_fmac_f32_e32 v10, v182, v130
	v_fmac_f32_e32 v8, v182, v131
	v_fmac_f32_e32 v13, v206, v128
	v_fmac_f32_e32 v11, v206, v129
	v_fmac_f32_e32 v9, v206, v130
	v_fmac_f32_e32 v7, v206, v131
	s_nop 0
	s_nop 0
	ds_read_b128 v[116:119], v65
	ds_read_b128 v[120:123], v65 offset:16
	ds_read_b128 v[124:127], v65 offset:32
	ds_read_b128 v[128:131], v65 offset:48
	s_waitcnt vmcnt(17) lgkmcnt(3)
	v_fmac_f32_e32 v114, v183, v116
	v_fmac_f32_e32 v112, v183, v117
	s_waitcnt vmcnt(16)
	v_fmac_f32_e32 v113, v207, v116
	v_fmac_f32_e32 v111, v207, v117
	v_or_b32_e32 v116, v2, v66
	v_mov_b32_e32 v117, v3
	v_lshl_add_u64 v[116:117], v[116:117], 2, s[52:53]
	v_fmac_f32_e32 v110, v183, v118
	v_fmac_f32_e32 v108, v183, v119
	v_fmac_f32_e32 v109, v207, v118
	v_fmac_f32_e32 v107, v207, v119
	s_waitcnt lgkmcnt(2)
	v_fmac_f32_e32 v106, v183, v120
	v_fmac_f32_e32 v104, v183, v121
	v_fmac_f32_e32 v102, v183, v122
	v_fmac_f32_e32 v100, v183, v123
	v_fmac_f32_e32 v105, v207, v120
	v_fmac_f32_e32 v103, v207, v121
	v_fmac_f32_e32 v101, v207, v122
	v_fmac_f32_e32 v99, v207, v123
	s_waitcnt lgkmcnt(1)
	v_fmac_f32_e32 v98, v183, v124
	v_fmac_f32_e32 v96, v183, v125
	v_fmac_f32_e32 v93, v183, v126
	v_fmac_f32_e32 v16, v183, v127
	v_fmac_f32_e32 v97, v207, v124
	v_fmac_f32_e32 v95, v207, v125
	v_fmac_f32_e32 v17, v207, v126
	v_fmac_f32_e32 v15, v207, v127
	s_waitcnt lgkmcnt(0)
	v_fmac_f32_e32 v14, v183, v128
	v_fmac_f32_e32 v12, v183, v129
	v_fmac_f32_e32 v10, v183, v130
	v_fmac_f32_e32 v8, v183, v131
	v_fmac_f32_e32 v13, v207, v128
	v_fmac_f32_e32 v11, v207, v129
	v_fmac_f32_e32 v9, v207, v130
	v_fmac_f32_e32 v7, v207, v131
	s_nop 0
	s_nop 0
	ds_read_b128 v[116:119], v67
	ds_read_b128 v[120:123], v67 offset:16
	ds_read_b128 v[124:127], v67 offset:32
	ds_read_b128 v[128:131], v67 offset:48
	s_waitcnt vmcnt(15) lgkmcnt(3)
	v_fmac_f32_e32 v114, v184, v116
	v_fmac_f32_e32 v112, v184, v117
	s_waitcnt vmcnt(14)
	v_fmac_f32_e32 v113, v208, v116
	v_fmac_f32_e32 v111, v208, v117
	v_or_b32_e32 v116, v2, v68
	v_mov_b32_e32 v117, v3
	v_lshl_add_u64 v[116:117], v[116:117], 2, s[52:53]
	v_fmac_f32_e32 v110, v184, v118
	v_fmac_f32_e32 v108, v184, v119
	v_fmac_f32_e32 v109, v208, v118
	v_fmac_f32_e32 v107, v208, v119
	s_waitcnt lgkmcnt(2)
	v_fmac_f32_e32 v106, v184, v120
	v_fmac_f32_e32 v104, v184, v121
	v_fmac_f32_e32 v102, v184, v122
	v_fmac_f32_e32 v100, v184, v123
	v_fmac_f32_e32 v105, v208, v120
	v_fmac_f32_e32 v103, v208, v121
	v_fmac_f32_e32 v101, v208, v122
	v_fmac_f32_e32 v99, v208, v123
	s_waitcnt lgkmcnt(1)
	v_fmac_f32_e32 v98, v184, v124
	v_fmac_f32_e32 v96, v184, v125
	v_fmac_f32_e32 v93, v184, v126
	v_fmac_f32_e32 v16, v184, v127
	v_fmac_f32_e32 v97, v208, v124
	v_fmac_f32_e32 v95, v208, v125
	v_fmac_f32_e32 v17, v208, v126
	v_fmac_f32_e32 v15, v208, v127
	s_waitcnt lgkmcnt(0)
	v_fmac_f32_e32 v14, v184, v128
	v_fmac_f32_e32 v12, v184, v129
	v_fmac_f32_e32 v10, v184, v130
	v_fmac_f32_e32 v8, v184, v131
	v_fmac_f32_e32 v13, v208, v128
	v_fmac_f32_e32 v11, v208, v129
	v_fmac_f32_e32 v9, v208, v130
	v_fmac_f32_e32 v7, v208, v131
	s_nop 0
	s_nop 0
	ds_read_b128 v[116:119], v69
	ds_read_b128 v[120:123], v69 offset:16
	ds_read_b128 v[124:127], v69 offset:32
	ds_read_b128 v[128:131], v69 offset:48
	s_waitcnt vmcnt(13) lgkmcnt(3)
	v_fmac_f32_e32 v114, v185, v116
	v_fmac_f32_e32 v112, v185, v117
	s_waitcnt vmcnt(12)
	v_fmac_f32_e32 v113, v209, v116
	v_fmac_f32_e32 v111, v209, v117
	v_or_b32_e32 v116, v2, v70
	v_mov_b32_e32 v117, v3
	v_lshl_add_u64 v[116:117], v[116:117], 2, s[52:53]
	v_fmac_f32_e32 v110, v185, v118
	v_fmac_f32_e32 v108, v185, v119
	v_fmac_f32_e32 v109, v209, v118
	v_fmac_f32_e32 v107, v209, v119
	s_waitcnt lgkmcnt(2)
	v_fmac_f32_e32 v106, v185, v120
	v_fmac_f32_e32 v104, v185, v121
	v_fmac_f32_e32 v102, v185, v122
	v_fmac_f32_e32 v100, v185, v123
	v_fmac_f32_e32 v105, v209, v120
	v_fmac_f32_e32 v103, v209, v121
	v_fmac_f32_e32 v101, v209, v122
	v_fmac_f32_e32 v99, v209, v123
	s_waitcnt lgkmcnt(1)
	v_fmac_f32_e32 v98, v185, v124
	v_fmac_f32_e32 v96, v185, v125
	v_fmac_f32_e32 v93, v185, v126
	v_fmac_f32_e32 v16, v185, v127
	v_fmac_f32_e32 v97, v209, v124
	v_fmac_f32_e32 v95, v209, v125
	v_fmac_f32_e32 v17, v209, v126
	v_fmac_f32_e32 v15, v209, v127
	s_waitcnt lgkmcnt(0)
	v_fmac_f32_e32 v14, v185, v128
	v_fmac_f32_e32 v12, v185, v129
	v_fmac_f32_e32 v10, v185, v130
	v_fmac_f32_e32 v8, v185, v131
	v_fmac_f32_e32 v13, v209, v128
	v_fmac_f32_e32 v11, v209, v129
	v_fmac_f32_e32 v9, v209, v130
	v_fmac_f32_e32 v7, v209, v131
	s_nop 0
	s_nop 0
	ds_read_b128 v[116:119], v71
	ds_read_b128 v[120:123], v71 offset:16
	ds_read_b128 v[124:127], v71 offset:32
	ds_read_b128 v[128:131], v71 offset:48
	s_waitcnt vmcnt(11) lgkmcnt(3)
	v_fmac_f32_e32 v114, v186, v116
	v_fmac_f32_e32 v112, v186, v117
	s_waitcnt vmcnt(10)
	v_fmac_f32_e32 v113, v210, v116
	v_fmac_f32_e32 v111, v210, v117
	v_or_b32_e32 v116, v2, v72
	v_mov_b32_e32 v117, v3
	v_lshl_add_u64 v[116:117], v[116:117], 2, s[52:53]
	v_fmac_f32_e32 v110, v186, v118
	v_fmac_f32_e32 v108, v186, v119
	v_fmac_f32_e32 v109, v210, v118
	v_fmac_f32_e32 v107, v210, v119
	s_waitcnt lgkmcnt(2)
	v_fmac_f32_e32 v106, v186, v120
	v_fmac_f32_e32 v104, v186, v121
	v_fmac_f32_e32 v102, v186, v122
	v_fmac_f32_e32 v100, v186, v123
	v_fmac_f32_e32 v105, v210, v120
	v_fmac_f32_e32 v103, v210, v121
	v_fmac_f32_e32 v101, v210, v122
	v_fmac_f32_e32 v99, v210, v123
	s_waitcnt lgkmcnt(1)
	v_fmac_f32_e32 v98, v186, v124
	v_fmac_f32_e32 v96, v186, v125
	v_fmac_f32_e32 v93, v186, v126
	v_fmac_f32_e32 v16, v186, v127
	v_fmac_f32_e32 v97, v210, v124
	v_fmac_f32_e32 v95, v210, v125
	v_fmac_f32_e32 v17, v210, v126
	v_fmac_f32_e32 v15, v210, v127
	s_waitcnt lgkmcnt(0)
; #define LAS __attribute__((address_space(3)))
; DI void gla_gate_phase(int wv, LAS unsigned char* lds, const float* x, const float* w_in, const float* w2, const float* bg, const bf16_t* qk1,
;                        bf16_t* qd, bf16_t* ki, bf16_t* kst, float* decay, bf16_t* sbuf) {
;     ...
;             for (int i = 0; i < 16; ++i) { const int k = lane + 64 * i; const float x0 = x[t0 * DM + k], x1 = x[(t0 + 1) * DM + k];
; #pragma unroll
;                 for (int q = 0; q < 4; ++q) { const f32x4 w = *(const LAS f32x4*)(wg + k * 16 + 4 * q);
;                     a0[4 * q] += x0 * w.x; a0[4 * q + 1] += x0 * w.y; a0[4 * q + 2] += x0 * w.z; a0[4 * q + 3] += x0 * w.w;
;                     a1[4 * q] += x1 * w.x; a1[4 * q + 1] += x1 * w.y; a1[4 * q + 2] += x1 * w.z; a1[4 * q + 3] += x1 * w.w; } }
	v_fmac_f32_e32 v14, v186, v128
	v_fmac_f32_e32 v12, v186, v129
	v_fmac_f32_e32 v10, v186, v130
	v_fmac_f32_e32 v8, v186, v131
	v_fmac_f32_e32 v13, v210, v128
	v_fmac_f32_e32 v11, v210, v129
	v_fmac_f32_e32 v9, v210, v130
	v_fmac_f32_e32 v7, v210, v131
	s_nop 0
	s_nop 0
	ds_read_b128 v[116:119], v73
	ds_read_b128 v[120:123], v73 offset:16
	ds_read_b128 v[124:127], v73 offset:32
	ds_read_b128 v[128:131], v73 offset:48
	s_waitcnt vmcnt(9) lgkmcnt(3)
	v_fmac_f32_e32 v114, v187, v116
	v_fmac_f32_e32 v112, v187, v117
	s_waitcnt vmcnt(8)
	v_fmac_f32_e32 v113, v211, v116
	v_fmac_f32_e32 v111, v211, v117
	v_or_b32_e32 v116, v2, v74
	v_mov_b32_e32 v117, v3
	v_lshl_add_u64 v[116:117], v[116:117], 2, s[52:53]
	v_fmac_f32_e32 v110, v187, v118
	v_fmac_f32_e32 v108, v187, v119
	v_fmac_f32_e32 v109, v211, v118
	v_fmac_f32_e32 v107, v211, v119
	s_waitcnt lgkmcnt(2)
	v_fmac_f32_e32 v106, v187, v120
	v_fmac_f32_e32 v104, v187, v121
	v_fmac_f32_e32 v102, v187, v122
	v_fmac_f32_e32 v100, v187, v123
	v_fmac_f32_e32 v105, v211, v120
	v_fmac_f32_e32 v103, v211, v121
	v_fmac_f32_e32 v101, v211, v122
	v_fmac_f32_e32 v99, v211, v123
	s_waitcnt lgkmcnt(1)
	v_fmac_f32_e32 v98, v187, v124
	v_fmac_f32_e32 v96, v187, v125
	v_fmac_f32_e32 v93, v187, v126
	v_fmac_f32_e32 v16, v187, v127
	v_fmac_f32_e32 v97, v211, v124
	v_fmac_f32_e32 v95, v211, v125
	v_fmac_f32_e32 v17, v211, v126
	v_fmac_f32_e32 v15, v211, v127
	s_waitcnt lgkmcnt(0)
	v_fmac_f32_e32 v14, v187, v128
	v_fmac_f32_e32 v12, v187, v129
	v_fmac_f32_e32 v10, v187, v130
	v_fmac_f32_e32 v8, v187, v131
	v_fmac_f32_e32 v13, v211, v128
	v_fmac_f32_e32 v11, v211, v129
	v_fmac_f32_e32 v9, v211, v130
	v_fmac_f32_e32 v7, v211, v131
	s_nop 0
	s_nop 0
	ds_read_b128 v[116:119], v75
	ds_read_b128 v[120:123], v75 offset:16
	ds_read_b128 v[124:127], v75 offset:32
	ds_read_b128 v[128:131], v75 offset:48
	s_waitcnt vmcnt(7) lgkmcnt(3)
	v_fmac_f32_e32 v114, v188, v116
	v_fmac_f32_e32 v112, v188, v117
	s_waitcnt vmcnt(6)
	v_fmac_f32_e32 v113, v212, v116
	v_fmac_f32_e32 v111, v212, v117
	v_or_b32_e32 v116, v2, v76
	v_mov_b32_e32 v117, v3
	v_lshl_add_u64 v[116:117], v[116:117], 2, s[52:53]
	v_fmac_f32_e32 v110, v188, v118
	v_fmac_f32_e32 v108, v188, v119
	v_fmac_f32_e32 v109, v212, v118
	v_fmac_f32_e32 v107, v212, v119
	s_waitcnt lgkmcnt(2)
	v_fmac_f32_e32 v106, v188, v120
	v_fmac_f32_e32 v104, v188, v121
	v_fmac_f32_e32 v102, v188, v122
	v_fmac_f32_e32 v100, v188, v123
	v_fmac_f32_e32 v105, v212, v120
	v_fmac_f32_e32 v103, v212, v121
	v_fmac_f32_e32 v101, v212, v122
	v_fmac_f32_e32 v99, v212, v123
	s_waitcnt lgkmcnt(1)
	v_fmac_f32_e32 v98, v188, v124
	v_fmac_f32_e32 v96, v188, v125
	v_fmac_f32_e32 v93, v188, v126
	v_fmac_f32_e32 v16, v188, v127
	v_fmac_f32_e32 v97, v212, v124
	v_fmac_f32_e32 v95, v212, v125
	v_fmac_f32_e32 v17, v212, v126
	v_fmac_f32_e32 v15, v212, v127
	s_waitcnt lgkmcnt(0)
	v_fmac_f32_e32 v14, v188, v128
	v_fmac_f32_e32 v12, v188, v129
	v_fmac_f32_e32 v10, v188, v130
	v_fmac_f32_e32 v8, v188, v131
	v_fmac_f32_e32 v13, v212, v128
	v_fmac_f32_e32 v11, v212, v129
	v_fmac_f32_e32 v9, v212, v130
	v_fmac_f32_e32 v7, v212, v131
	s_nop 0
	s_nop 0
	ds_read_b128 v[116:119], v77
	ds_read_b128 v[120:123], v77 offset:16
	ds_read_b128 v[124:127], v77 offset:32
	ds_read_b128 v[128:131], v77 offset:48
	s_waitcnt vmcnt(5) lgkmcnt(3)
	v_fmac_f32_e32 v114, v189, v116
	v_fmac_f32_e32 v112, v189, v117
	s_waitcnt vmcnt(4)
	v_fmac_f32_e32 v113, v213, v116
	v_fmac_f32_e32 v111, v213, v117
	v_or_b32_e32 v116, v2, v78
	v_mov_b32_e32 v117, v3
	v_lshl_add_u64 v[116:117], v[116:117], 2, s[52:53]
	v_fmac_f32_e32 v110, v189, v118
	v_fmac_f32_e32 v108, v189, v119
	v_fmac_f32_e32 v109, v213, v118
	v_fmac_f32_e32 v107, v213, v119
	s_waitcnt lgkmcnt(2)
	v_fmac_f32_e32 v106, v189, v120
	v_fmac_f32_e32 v104, v189, v121
	v_fmac_f32_e32 v102, v189, v122
	v_fmac_f32_e32 v100, v189, v123
	v_fmac_f32_e32 v105, v213, v120
	v_fmac_f32_e32 v103, v213, v121
	v_fmac_f32_e32 v101, v213, v122
	v_fmac_f32_e32 v99, v213, v123
	s_waitcnt lgkmcnt(1)
	v_fmac_f32_e32 v98, v189, v124
	v_fmac_f32_e32 v96, v189, v125
	v_fmac_f32_e32 v93, v189, v126
	v_fmac_f32_e32 v16, v189, v127
	v_fmac_f32_e32 v97, v213, v124
	v_fmac_f32_e32 v95, v213, v125
	v_fmac_f32_e32 v17, v213, v126
	v_fmac_f32_e32 v15, v213, v127
	s_waitcnt lgkmcnt(0)
	v_fmac_f32_e32 v14, v189, v128
	v_fmac_f32_e32 v12, v189, v129
	v_fmac_f32_e32 v10, v189, v130
	v_fmac_f32_e32 v8, v189, v131
	v_fmac_f32_e32 v13, v213, v128
	v_fmac_f32_e32 v11, v213, v129
	v_fmac_f32_e32 v9, v213, v130
	v_fmac_f32_e32 v7, v213, v131
	s_nop 0
	s_nop 0
	ds_read_b128 v[116:119], v79
	ds_read_b128 v[120:123], v79 offset:16
	ds_read_b128 v[124:127], v79 offset:32
	ds_read_b128 v[128:131], v79 offset:48
	s_waitcnt vmcnt(3) lgkmcnt(3)
	v_fmac_f32_e32 v114, v190, v116
	v_fmac_f32_e32 v112, v190, v117
	s_waitcnt vmcnt(2)
	v_fmac_f32_e32 v113, v214, v116
	v_fmac_f32_e32 v111, v214, v117
	v_or_b32_e32 v116, v2, v80
	v_mov_b32_e32 v117, v3
	v_lshl_add_u64 v[116:117], v[116:117], 2, s[52:53]
	v_fmac_f32_e32 v110, v190, v118
	v_fmac_f32_e32 v108, v190, v119
	v_fmac_f32_e32 v109, v214, v118
	v_fmac_f32_e32 v107, v214, v119
	s_waitcnt lgkmcnt(2)
	v_fmac_f32_e32 v106, v190, v120
	v_fmac_f32_e32 v104, v190, v121
	v_fmac_f32_e32 v102, v190, v122
	v_fmac_f32_e32 v100, v190, v123
	v_fmac_f32_e32 v105, v214, v120
	v_fmac_f32_e32 v103, v214, v121
	v_fmac_f32_e32 v101, v214, v122
	v_fmac_f32_e32 v99, v214, v123
	s_waitcnt lgkmcnt(1)
	v_fmac_f32_e32 v98, v190, v124
	v_fmac_f32_e32 v96, v190, v125
	v_fmac_f32_e32 v93, v190, v126
	v_fmac_f32_e32 v16, v190, v127
	v_fmac_f32_e32 v97, v214, v124
	v_fmac_f32_e32 v95, v214, v125
	v_fmac_f32_e32 v17, v214, v126
	v_fmac_f32_e32 v15, v214, v127
	s_waitcnt lgkmcnt(0)
; #define LAS __attribute__((address_space(3)))
; DI float wave_sum(float v) {
; #pragma unroll
;     for (int o = 1; o < 64; o <<= 1) v += __shfl_xor(v, o);
;     return v;
; DI void gla_gate_phase(int wv, LAS unsigned char* lds, const float* x, const float* w_in, const float* w2, const float* bg, const bf16_t* qk1,
;                        bf16_t* qd, bf16_t* ki, bf16_t* kst, float* decay, bf16_t* sbuf) {
;     ...
;             for (int i = 0; i < 16; ++i) { const int k = lane + 64 * i; const float x0 = x[t0 * DM + k], x1 = x[(t0 + 1) * DM + k];
; #pragma unroll
;                 for (int q = 0; q < 4; ++q) { const f32x4 w = *(const LAS f32x4*)(wg + k * 16 + 4 * q);
;                     a0[4 * q] += x0 * w.x; a0[4 * q + 1] += x0 * w.y; a0[4 * q + 2] += x0 * w.z; a0[4 * q + 3] += x0 * w.w;
;                     a1[4 * q] += x1 * w.x; a1[4 * q + 1] += x1 * w.y; a1[4 * q + 2] += x1 * w.z; a1[4 * q + 3] += x1 * w.w; } }
;             float v0 = 0.f, v1 = 0.f;
; #pragma unroll
;             for (int n = 0; n < 16; ++n) { const float s0 = wave_sum(a0[n]), s1 = wave_sum(a1[n]); v0 = (lane == n) ? s0 : v0; v1 = (lane == n) ? s1 : v1; }
	v_fmac_f32_e32 v14, v190, v128
	v_fmac_f32_e32 v12, v190, v129
	v_fmac_f32_e32 v10, v190, v130
	v_fmac_f32_e32 v8, v190, v131
	v_fmac_f32_e32 v13, v214, v128
	v_fmac_f32_e32 v11, v214, v129
	v_fmac_f32_e32 v9, v214, v130
	v_fmac_f32_e32 v7, v214, v131
	s_nop 0
	s_nop 0
	ds_read_b128 v[116:119], v81
	ds_read_b128 v[120:123], v81 offset:16
	ds_read_b128 v[124:127], v81 offset:32
	ds_read_b128 v[128:131], v81 offset:48
	s_waitcnt vmcnt(1) lgkmcnt(3)
	v_fmac_f32_e32 v114, v191, v116
	v_fmac_f32_e32 v112, v191, v117
	v_fmac_f32_e32 v110, v191, v118
	v_fmac_f32_e32 v108, v191, v119
	s_waitcnt vmcnt(0)
	v_fmac_f32_e32 v113, v215, v116
	v_fmac_f32_e32 v111, v215, v117
	v_fmac_f32_e32 v109, v215, v118
	v_fmac_f32_e32 v107, v215, v119
	s_waitcnt lgkmcnt(2)
	v_fmac_f32_e32 v106, v191, v120
	v_fmac_f32_e32 v104, v191, v121
	v_fmac_f32_e32 v102, v191, v122
	v_fmac_f32_e32 v100, v191, v123
	v_fmac_f32_e32 v105, v215, v120
	v_fmac_f32_e32 v103, v215, v121
	v_fmac_f32_e32 v101, v215, v122
	v_fmac_f32_e32 v99, v215, v123
	s_waitcnt lgkmcnt(1)
	v_fmac_f32_e32 v98, v191, v124
	v_fmac_f32_e32 v96, v191, v125
	v_fmac_f32_e32 v93, v191, v126
	v_fmac_f32_e32 v16, v191, v127
	v_fmac_f32_e32 v97, v215, v124
	v_fmac_f32_e32 v95, v215, v125
	v_fmac_f32_e32 v17, v215, v126
	v_fmac_f32_e32 v15, v215, v127
	s_waitcnt lgkmcnt(0)
	v_fmac_f32_e32 v14, v191, v128
	v_fmac_f32_e32 v12, v191, v129
	v_fmac_f32_e32 v10, v191, v130
	v_fmac_f32_e32 v8, v191, v131
	v_fmac_f32_e32 v13, v215, v128
	v_fmac_f32_e32 v11, v215, v129
	v_fmac_f32_e32 v9, v215, v130
	v_fmac_f32_e32 v7, v215, v131
	ds_bpermute_b32 v115, v233, v114
	ds_bpermute_b32 v116, v233, v113
	ds_bpermute_b32 v117, v233, v112
	ds_bpermute_b32 v118, v233, v111
	ds_bpermute_b32 v119, v233, v110
	ds_bpermute_b32 v120, v233, v109
	ds_bpermute_b32 v121, v233, v108
	ds_bpermute_b32 v122, v233, v107
	ds_bpermute_b32 v123, v233, v106
	ds_bpermute_b32 v124, v233, v105
	ds_bpermute_b32 v125, v233, v104
	ds_bpermute_b32 v126, v233, v103
	ds_bpermute_b32 v127, v233, v102
	ds_bpermute_b32 v128, v233, v101
	ds_bpermute_b32 v129, v233, v100
	ds_bpermute_b32 v130, v233, v99
	ds_bpermute_b32 v131, v233, v98
	ds_bpermute_b32 v132, v233, v97
	ds_bpermute_b32 v133, v233, v96
	ds_bpermute_b32 v134, v233, v95
	ds_bpermute_b32 v135, v233, v93
	ds_bpermute_b32 v136, v233, v17
	ds_bpermute_b32 v137, v233, v16
	ds_bpermute_b32 v138, v233, v15
	ds_bpermute_b32 v139, v233, v14
	ds_bpermute_b32 v140, v233, v13
	ds_bpermute_b32 v141, v233, v12
	ds_bpermute_b32 v142, v233, v11
	ds_bpermute_b32 v143, v233, v10
	ds_bpermute_b32 v144, v233, v9
	ds_bpermute_b32 v145, v233, v8
	ds_bpermute_b32 v146, v233, v7
	s_waitcnt lgkmcnt(14)
	v_add_f32_e32 v114, v114, v115
	v_add_f32_e32 v113, v113, v116
	v_add_f32_e32 v112, v112, v117
	v_add_f32_e32 v111, v111, v118
	v_add_f32_e32 v110, v110, v119
	v_add_f32_e32 v109, v109, v120
	v_add_f32_e32 v108, v108, v121
	v_add_f32_e32 v107, v107, v122
	v_add_f32_e32 v106, v106, v123
	v_add_f32_e32 v105, v105, v124
	v_add_f32_e32 v104, v104, v125
	v_add_f32_e32 v103, v103, v126
	v_add_f32_e32 v102, v102, v127
	v_add_f32_e32 v101, v101, v128
	v_add_f32_e32 v100, v100, v129
	v_add_f32_e32 v99, v99, v130
	v_add_f32_e32 v98, v98, v131
	v_add_f32_e32 v97, v97, v132
	s_waitcnt lgkmcnt(13)
	v_add_f32_e32 v96, v96, v133
	s_waitcnt lgkmcnt(12)
	v_add_f32_e32 v95, v95, v134
	s_waitcnt lgkmcnt(11)
	v_add_f32_e32 v93, v93, v135
	s_waitcnt lgkmcnt(10)
	v_add_f32_e32 v17, v17, v136
	s_waitcnt lgkmcnt(9)
	v_add_f32_e32 v16, v16, v137
	s_waitcnt lgkmcnt(8)
	v_add_f32_e32 v15, v15, v138
	s_waitcnt lgkmcnt(7)
	v_add_f32_e32 v14, v14, v139
	s_waitcnt lgkmcnt(6)
	v_add_f32_e32 v13, v13, v140
	s_waitcnt lgkmcnt(5)
	v_add_f32_e32 v12, v12, v141
	s_waitcnt lgkmcnt(4)
	v_add_f32_e32 v11, v11, v142
	s_waitcnt lgkmcnt(3)
	v_add_f32_e32 v10, v10, v143
	s_waitcnt lgkmcnt(2)
	v_add_f32_e32 v9, v9, v144
	s_waitcnt lgkmcnt(1)
	v_add_f32_e32 v8, v8, v145
	s_waitcnt lgkmcnt(0)
	v_add_f32_e32 v7, v7, v146
	ds_bpermute_b32 v115, v234, v114
	ds_bpermute_b32 v116, v234, v113
	ds_bpermute_b32 v117, v234, v112
	ds_bpermute_b32 v118, v234, v111
	ds_bpermute_b32 v119, v234, v110
	ds_bpermute_b32 v120, v234, v109
	ds_bpermute_b32 v121, v234, v108
	ds_bpermute_b32 v122, v234, v107
	ds_bpermute_b32 v123, v234, v106
	ds_bpermute_b32 v124, v234, v105
	ds_bpermute_b32 v125, v234, v104
	ds_bpermute_b32 v126, v234, v103
	ds_bpermute_b32 v127, v234, v102
	ds_bpermute_b32 v128, v234, v101
	ds_bpermute_b32 v129, v234, v100
	ds_bpermute_b32 v130, v234, v99
	ds_bpermute_b32 v131, v234, v98
	ds_bpermute_b32 v132, v234, v97
	ds_bpermute_b32 v133, v234, v96
	ds_bpermute_b32 v134, v234, v95
	ds_bpermute_b32 v135, v234, v93
	ds_bpermute_b32 v136, v234, v17
	ds_bpermute_b32 v137, v234, v16
	ds_bpermute_b32 v138, v234, v15
	ds_bpermute_b32 v139, v234, v14
	ds_bpermute_b32 v140, v234, v13
	ds_bpermute_b32 v141, v234, v12
	ds_bpermute_b32 v142, v234, v11
	ds_bpermute_b32 v143, v234, v10
	ds_bpermute_b32 v144, v234, v9
	ds_bpermute_b32 v145, v234, v8
	ds_bpermute_b32 v146, v234, v7
	s_waitcnt lgkmcnt(14)
	v_add_f32_e32 v114, v114, v115
	v_add_f32_e32 v113, v113, v116
	v_add_f32_e32 v112, v112, v117
	v_add_f32_e32 v111, v111, v118
	v_add_f32_e32 v110, v110, v119
	v_add_f32_e32 v109, v109, v120
	v_add_f32_e32 v108, v108, v121
	v_add_f32_e32 v107, v107, v122
	v_add_f32_e32 v106, v106, v123
	v_add_f32_e32 v105, v105, v124
	v_add_f32_e32 v104, v104, v125
	v_add_f32_e32 v103, v103, v126
	v_add_f32_e32 v102, v102, v127
	v_add_f32_e32 v101, v101, v128
	v_add_f32_e32 v100, v100, v129
	v_add_f32_e32 v99, v99, v130
	v_add_f32_e32 v98, v98, v131
	v_add_f32_e32 v97, v97, v132
	s_waitcnt lgkmcnt(13)
; DI float wave_sum(float v) {
; #pragma unroll
;     for (int o = 1; o < 64; o <<= 1) v += __shfl_xor(v, o);
;     return v;
; DI void gla_gate_phase(int wv, LAS unsigned char* lds, const float* x, const float* w_in, const float* w2, const float* bg, const bf16_t* qk1,
;                        bf16_t* qd, bf16_t* ki, bf16_t* kst, float* decay, bf16_t* sbuf) {
;     ...
;             for (int n = 0; n < 16; ++n) { const float s0 = wave_sum(a0[n]), s1 = wave_sum(a1[n]); v0 = (lane == n) ? s0 : v0; v1 = (lane == n) ? s1 : v1; }
	v_add_f32_e32 v96, v96, v133
	s_waitcnt lgkmcnt(12)
	v_add_f32_e32 v95, v95, v134
	s_waitcnt lgkmcnt(11)
	v_add_f32_e32 v93, v93, v135
	s_waitcnt lgkmcnt(10)
	v_add_f32_e32 v17, v17, v136
	s_waitcnt lgkmcnt(9)
	v_add_f32_e32 v16, v16, v137
	s_waitcnt lgkmcnt(8)
	v_add_f32_e32 v15, v15, v138
	s_waitcnt lgkmcnt(7)
	v_add_f32_e32 v14, v14, v139
	s_waitcnt lgkmcnt(6)
	v_add_f32_e32 v13, v13, v140
	s_waitcnt lgkmcnt(5)
	v_add_f32_e32 v12, v12, v141
	s_waitcnt lgkmcnt(4)
	v_add_f32_e32 v11, v11, v142
	s_waitcnt lgkmcnt(3)
	v_add_f32_e32 v10, v10, v143
	s_waitcnt lgkmcnt(2)
	v_add_f32_e32 v9, v9, v144
	s_waitcnt lgkmcnt(1)
	v_add_f32_e32 v8, v8, v145
	s_waitcnt lgkmcnt(0)
	v_add_f32_e32 v7, v7, v146
	ds_bpermute_b32 v115, v235, v114
	ds_bpermute_b32 v116, v235, v113
	ds_bpermute_b32 v117, v235, v112
	ds_bpermute_b32 v118, v235, v111
	ds_bpermute_b32 v119, v235, v110
	ds_bpermute_b32 v120, v235, v109
	ds_bpermute_b32 v121, v235, v108
	ds_bpermute_b32 v122, v235, v107
	ds_bpermute_b32 v123, v235, v106
	ds_bpermute_b32 v124, v235, v105
	ds_bpermute_b32 v125, v235, v104
	ds_bpermute_b32 v126, v235, v103
	ds_bpermute_b32 v127, v235, v102
	ds_bpermute_b32 v128, v235, v101
	ds_bpermute_b32 v129, v235, v100
	ds_bpermute_b32 v130, v235, v99
	ds_bpermute_b32 v131, v235, v98
	ds_bpermute_b32 v132, v235, v97
	ds_bpermute_b32 v133, v235, v96
	ds_bpermute_b32 v134, v235, v95
	ds_bpermute_b32 v135, v235, v93
	ds_bpermute_b32 v136, v235, v17
	ds_bpermute_b32 v137, v235, v16
	ds_bpermute_b32 v138, v235, v15
	ds_bpermute_b32 v139, v235, v14
	ds_bpermute_b32 v140, v235, v13
	ds_bpermute_b32 v141, v235, v12
	ds_bpermute_b32 v142, v235, v11
	ds_bpermute_b32 v143, v235, v10
	ds_bpermute_b32 v144, v235, v9
	ds_bpermute_b32 v145, v235, v8
	ds_bpermute_b32 v146, v235, v7
	s_waitcnt lgkmcnt(14)
	v_add_f32_e32 v114, v114, v115
	v_add_f32_e32 v113, v113, v116
	v_add_f32_e32 v112, v112, v117
	v_add_f32_e32 v111, v111, v118
	v_add_f32_e32 v110, v110, v119
	v_add_f32_e32 v109, v109, v120
	v_add_f32_e32 v108, v108, v121
	v_add_f32_e32 v107, v107, v122
	v_add_f32_e32 v106, v106, v123
	v_add_f32_e32 v105, v105, v124
	v_add_f32_e32 v104, v104, v125
	v_add_f32_e32 v103, v103, v126
	v_add_f32_e32 v102, v102, v127
	v_add_f32_e32 v101, v101, v128
	v_add_f32_e32 v100, v100, v129
	v_add_f32_e32 v99, v99, v130
	v_add_f32_e32 v98, v98, v131
	v_add_f32_e32 v97, v97, v132
	s_waitcnt lgkmcnt(13)
	v_add_f32_e32 v96, v96, v133
	s_waitcnt lgkmcnt(12)
	v_add_f32_e32 v95, v95, v134
	s_waitcnt lgkmcnt(11)
	v_add_f32_e32 v93, v93, v135
	s_waitcnt lgkmcnt(10)
	v_add_f32_e32 v17, v17, v136
	s_waitcnt lgkmcnt(9)
	v_add_f32_e32 v16, v16, v137
	s_waitcnt lgkmcnt(8)
	v_add_f32_e32 v15, v15, v138
	s_waitcnt lgkmcnt(7)
	v_add_f32_e32 v14, v14, v139
	s_waitcnt lgkmcnt(6)
	v_add_f32_e32 v13, v13, v140
	s_waitcnt lgkmcnt(5)
	v_add_f32_e32 v12, v12, v141
	s_waitcnt lgkmcnt(4)
	v_add_f32_e32 v11, v11, v142
	s_waitcnt lgkmcnt(3)
	v_add_f32_e32 v10, v10, v143
	s_waitcnt lgkmcnt(2)
	v_add_f32_e32 v9, v9, v144
	s_waitcnt lgkmcnt(1)
	v_add_f32_e32 v8, v8, v145
	s_waitcnt lgkmcnt(0)
	v_add_f32_e32 v7, v7, v146
	ds_bpermute_b32 v115, v236, v114
	ds_bpermute_b32 v116, v236, v113
	ds_bpermute_b32 v117, v236, v112
	ds_bpermute_b32 v118, v236, v111
	ds_bpermute_b32 v119, v236, v110
	ds_bpermute_b32 v120, v236, v109
	ds_bpermute_b32 v121, v236, v108
	ds_bpermute_b32 v122, v236, v107
	ds_bpermute_b32 v123, v236, v106
	ds_bpermute_b32 v124, v236, v105
	ds_bpermute_b32 v125, v236, v104
	ds_bpermute_b32 v126, v236, v103
	ds_bpermute_b32 v127, v236, v102
	ds_bpermute_b32 v128, v236, v101
	ds_bpermute_b32 v129, v236, v100
	ds_bpermute_b32 v130, v236, v99
	ds_bpermute_b32 v131, v236, v98
	ds_bpermute_b32 v132, v236, v97
	ds_bpermute_b32 v133, v236, v96
	ds_bpermute_b32 v134, v236, v95
	ds_bpermute_b32 v135, v236, v93
	ds_bpermute_b32 v136, v236, v17
	ds_bpermute_b32 v137, v236, v16
	ds_bpermute_b32 v138, v236, v15
	ds_bpermute_b32 v139, v236, v14
	ds_bpermute_b32 v140, v236, v13
	ds_bpermute_b32 v141, v236, v12
	ds_bpermute_b32 v142, v236, v11
	ds_bpermute_b32 v143, v236, v10
	ds_bpermute_b32 v144, v236, v9
	ds_bpermute_b32 v145, v236, v8
	ds_bpermute_b32 v146, v236, v7
	s_waitcnt lgkmcnt(14)
	v_add_f32_e32 v114, v114, v115
	v_add_f32_e32 v113, v113, v116
	v_add_f32_e32 v112, v112, v117
	v_add_f32_e32 v111, v111, v118
	v_add_f32_e32 v110, v110, v119
	v_add_f32_e32 v109, v109, v120
	v_add_f32_e32 v108, v108, v121
	v_add_f32_e32 v107, v107, v122
	v_add_f32_e32 v106, v106, v123
	v_add_f32_e32 v105, v105, v124
	v_add_f32_e32 v104, v104, v125
	v_add_f32_e32 v103, v103, v126
	v_add_f32_e32 v102, v102, v127
	v_add_f32_e32 v101, v101, v128
	v_add_f32_e32 v100, v100, v129
	v_add_f32_e32 v99, v99, v130
	v_add_f32_e32 v98, v98, v131
	v_add_f32_e32 v97, v97, v132
	s_waitcnt lgkmcnt(13)
	v_add_f32_e32 v96, v96, v133
	s_waitcnt lgkmcnt(12)
	v_add_f32_e32 v95, v95, v134
	s_waitcnt lgkmcnt(11)
	v_add_f32_e32 v93, v93, v135
	s_waitcnt lgkmcnt(10)
	v_add_f32_e32 v17, v17, v136
	s_waitcnt lgkmcnt(9)
	v_add_f32_e32 v16, v16, v137
	s_waitcnt lgkmcnt(8)
	v_add_f32_e32 v15, v15, v138
	s_waitcnt lgkmcnt(7)
	v_add_f32_e32 v14, v14, v139
	s_waitcnt lgkmcnt(6)
	v_add_f32_e32 v13, v13, v140
	s_waitcnt lgkmcnt(5)
	v_add_f32_e32 v12, v12, v141
	s_waitcnt lgkmcnt(4)
	v_add_f32_e32 v11, v11, v142
	s_waitcnt lgkmcnt(3)
	v_add_f32_e32 v10, v10, v143
	s_waitcnt lgkmcnt(2)
	v_add_f32_e32 v9, v9, v144
	s_waitcnt lgkmcnt(1)
	v_add_f32_e32 v8, v8, v145
	s_waitcnt lgkmcnt(0)
; DI float wave_sum(float v) {
; #pragma unroll
;     for (int o = 1; o < 64; o <<= 1) v += __shfl_xor(v, o);
;     return v;
; DI void gla_gate_phase(int wv, LAS unsigned char* lds, const float* x, const float* w_in, const float* w2, const float* bg, const bf16_t* qk1,
;                        bf16_t* qd, bf16_t* ki, bf16_t* kst, float* decay, bf16_t* sbuf) {
;     ...
;             for (int n = 0; n < 16; ++n) { const float s0 = wave_sum(a0[n]), s1 = wave_sum(a1[n]); v0 = (lane == n) ? s0 : v0; v1 = (lane == n) ? s1 : v1; }
;             if (lane < 16) { gl[(wid * 8 + tt) * 16 + lane] = v0; gl[(wid * 8 + tt + 1) * 16 + lane] = v1; }
	v_add_f32_e32 v7, v7, v146
	ds_bpermute_b32 v115, v237, v114
	ds_bpermute_b32 v116, v237, v113
	ds_bpermute_b32 v117, v237, v112
	ds_bpermute_b32 v118, v237, v111
	ds_bpermute_b32 v119, v237, v110
	ds_bpermute_b32 v120, v237, v109
	ds_bpermute_b32 v121, v237, v108
	ds_bpermute_b32 v122, v237, v107
	ds_bpermute_b32 v123, v237, v106
	ds_bpermute_b32 v124, v237, v105
	ds_bpermute_b32 v125, v237, v104
	ds_bpermute_b32 v126, v237, v103
	ds_bpermute_b32 v127, v237, v102
	ds_bpermute_b32 v128, v237, v101
	ds_bpermute_b32 v129, v237, v100
	ds_bpermute_b32 v130, v237, v99
	ds_bpermute_b32 v131, v237, v98
	ds_bpermute_b32 v132, v237, v97
	ds_bpermute_b32 v133, v237, v96
	ds_bpermute_b32 v134, v237, v95
	ds_bpermute_b32 v135, v237, v93
	ds_bpermute_b32 v136, v237, v17
	ds_bpermute_b32 v137, v237, v16
	ds_bpermute_b32 v138, v237, v15
	ds_bpermute_b32 v139, v237, v14
	ds_bpermute_b32 v140, v237, v13
	ds_bpermute_b32 v141, v237, v12
	ds_bpermute_b32 v142, v237, v11
	ds_bpermute_b32 v143, v237, v10
	ds_bpermute_b32 v144, v237, v9
	ds_bpermute_b32 v145, v237, v8
	ds_bpermute_b32 v146, v237, v7
	s_waitcnt lgkmcnt(14)
	v_add_f32_e32 v114, v114, v115
	v_add_f32_e32 v113, v113, v116
	v_add_f32_e32 v112, v112, v117
	v_add_f32_e32 v111, v111, v118
	v_add_f32_e32 v110, v110, v119
	v_add_f32_e32 v109, v109, v120
	v_add_f32_e32 v108, v108, v121
	v_add_f32_e32 v107, v107, v122
	v_add_f32_e32 v106, v106, v123
	v_add_f32_e32 v105, v105, v124
	v_add_f32_e32 v104, v104, v125
	v_add_f32_e32 v103, v103, v126
	v_add_f32_e32 v102, v102, v127
	v_add_f32_e32 v101, v101, v128
	v_add_f32_e32 v100, v100, v129
	v_add_f32_e32 v99, v99, v130
	v_add_f32_e32 v98, v98, v131
	v_add_f32_e32 v97, v97, v132
	s_waitcnt lgkmcnt(13)
	v_add_f32_e32 v96, v96, v133
	s_waitcnt lgkmcnt(12)
	v_add_f32_e32 v95, v95, v134
	s_waitcnt lgkmcnt(11)
	v_add_f32_e32 v93, v93, v135
	s_waitcnt lgkmcnt(10)
	v_add_f32_e32 v17, v17, v136
	s_waitcnt lgkmcnt(9)
	v_add_f32_e32 v16, v16, v137
	s_waitcnt lgkmcnt(8)
	v_add_f32_e32 v15, v15, v138
	s_waitcnt lgkmcnt(7)
	v_add_f32_e32 v14, v14, v139
	s_waitcnt lgkmcnt(6)
	v_add_f32_e32 v13, v13, v140
	s_waitcnt lgkmcnt(5)
	v_add_f32_e32 v12, v12, v141
	s_waitcnt lgkmcnt(4)
	v_add_f32_e32 v11, v11, v142
	s_waitcnt lgkmcnt(3)
	v_add_f32_e32 v10, v10, v143
	s_waitcnt lgkmcnt(2)
	v_add_f32_e32 v9, v9, v144
	s_waitcnt lgkmcnt(1)
	v_add_f32_e32 v8, v8, v145
	s_waitcnt lgkmcnt(0)
	v_add_f32_e32 v7, v7, v146
	ds_bpermute_b32 v115, v238, v114
	ds_bpermute_b32 v116, v238, v113
	ds_bpermute_b32 v117, v238, v112
	ds_bpermute_b32 v118, v238, v111
	ds_bpermute_b32 v119, v238, v110
	ds_bpermute_b32 v120, v238, v109
	ds_bpermute_b32 v121, v238, v108
	ds_bpermute_b32 v122, v238, v107
	ds_bpermute_b32 v123, v238, v106
	ds_bpermute_b32 v124, v238, v105
	ds_bpermute_b32 v125, v238, v104
	ds_bpermute_b32 v126, v238, v103
	ds_bpermute_b32 v127, v238, v102
	ds_bpermute_b32 v128, v238, v101
	ds_bpermute_b32 v129, v238, v100
	ds_bpermute_b32 v130, v238, v99
	ds_bpermute_b32 v131, v238, v98
	ds_bpermute_b32 v132, v238, v97
	ds_bpermute_b32 v133, v238, v96
	ds_bpermute_b32 v134, v238, v95
	ds_bpermute_b32 v135, v238, v93
	ds_bpermute_b32 v136, v238, v17
	ds_bpermute_b32 v137, v238, v16
	ds_bpermute_b32 v138, v238, v15
	ds_bpermute_b32 v139, v238, v14
	ds_bpermute_b32 v140, v238, v13
	ds_bpermute_b32 v141, v238, v12
	ds_bpermute_b32 v142, v238, v11
	ds_bpermute_b32 v143, v238, v10
	ds_bpermute_b32 v144, v238, v9
	ds_bpermute_b32 v145, v238, v8
	ds_bpermute_b32 v146, v238, v7
	s_and_saveexec_b64 s[44:45], s[42:43]
	s_cbranch_execz .LBB0_142
	s_waitcnt lgkmcnt(14)
	v_add_f32_e32 v113, v113, v116
	v_add_f32_e32 v111, v111, v118
	v_cndmask_b32_e64 v113, 0, v113, s[40:41]
	v_add_f32_e32 v109, v109, v120
	v_cndmask_b32_e64 v111, v113, v111, s[38:39]
	v_add_f32_e32 v107, v107, v122
	v_cndmask_b32_e64 v109, v111, v109, s[36:37]
	v_add_f32_e32 v105, v105, v124
	v_cndmask_b32_e64 v107, v109, v107, s[34:35]
	v_add_f32_e32 v103, v103, v126
	v_cndmask_b32_e64 v105, v107, v105, s[30:31]
	v_add_f32_e32 v101, v101, v128
	v_cndmask_b32_e64 v103, v105, v103, s[28:29]
	v_add_f32_e32 v99, v99, v130
	v_cndmask_b32_e64 v101, v103, v101, s[26:27]
	v_add_f32_e32 v97, v97, v132
	v_cndmask_b32_e64 v99, v101, v99, s[24:25]
	s_waitcnt lgkmcnt(12)
	v_add_f32_e32 v95, v95, v134
	v_cndmask_b32_e64 v97, v99, v97, s[22:23]
	s_waitcnt lgkmcnt(10)
	v_add_f32_e32 v17, v17, v136
	v_cndmask_b32_e64 v95, v97, v95, s[20:21]
	s_waitcnt lgkmcnt(8)
	v_add_f32_e32 v15, v15, v138
	v_cndmask_b32_e64 v17, v95, v17, s[18:19]
	s_waitcnt lgkmcnt(6)
	v_add_f32_e32 v13, v13, v140
	v_cndmask_b32_e64 v15, v17, v15, s[16:17]
	v_add_f32_e32 v99, v114, v115
	s_waitcnt lgkmcnt(4)
	v_add_f32_e32 v11, v11, v142
	v_cndmask_b32_e64 v13, v15, v13, s[14:15]
	v_add_f32_e32 v15, v98, v131
	v_add_f32_e32 v98, v112, v117
	v_cndmask_b32_e64 v99, 0, v99, s[40:41]
	s_waitcnt lgkmcnt(2)
	v_add_f32_e32 v9, v9, v144
	v_cndmask_b32_e64 v11, v13, v11, s[12:13]
	v_add_f32_e32 v97, v110, v119
	v_cndmask_b32_e64 v98, v99, v98, s[38:39]
	v_cndmask_b32_e64 v9, v11, v9, s[10:11]
	v_add_f32_e32 v11, v14, v139
	v_add_f32_e32 v14, v96, v133
	v_add_f32_e32 v96, v108, v121
	v_cndmask_b32_e64 v97, v98, v97, s[36:37]
	v_add_f32_e32 v95, v106, v123
	v_cndmask_b32_e64 v96, v97, v96, s[34:35]
	v_add_f32_e32 v13, v93, v135
	v_add_f32_e32 v93, v104, v125
	v_cndmask_b32_e64 v95, v96, v95, s[30:31]
	s_waitcnt lgkmcnt(0)
	v_add_f32_e32 v7, v7, v146
	v_add_f32_e32 v17, v102, v127
	v_cndmask_b32_e64 v93, v95, v93, s[28:29]
	v_cndmask_b32_e64 v7, v9, v7, s[8:9]
	v_add_f32_e32 v9, v10, v143
	v_add_f32_e32 v10, v12, v141
	v_add_f32_e32 v12, v16, v137
	v_add_f32_e32 v16, v100, v129
	v_cndmask_b32_e64 v17, v93, v17, s[26:27]
	v_cndmask_b32_e64 v16, v17, v16, s[24:25]
	v_cndmask_b32_e64 v15, v16, v15, s[22:23]
	v_cndmask_b32_e64 v14, v15, v14, s[20:21]
	v_cndmask_b32_e64 v13, v14, v13, s[18:19]
	v_cndmask_b32_e64 v12, v13, v12, s[16:17]
	v_cndmask_b32_e64 v11, v12, v11, s[14:15]
	v_cndmask_b32_e64 v10, v11, v10, s[12:13]
	v_add_f32_e32 v8, v8, v145
	v_cndmask_b32_e64 v9, v10, v9, s[10:11]
	v_cndmask_b32_e64 v8, v9, v8, s[8:9]
	ds_write2_b32 v6, v8, v7 offset1:16
	s_branch .LBB0_142
